# attention set-up key-norm loop: eight row loads per iteration issued together with counted vmcnt waits instead of one load per vmcnt(0)
# baseline (speedup 1.0000x reference)
.LBB0_43:
	v_add_co_u32_e32 v78, vcc, 0xffdd0000, v8
	s_nop 1
	v_addc_co_u32_e32 v79, vcc, -1, v9, vcc
	global_load_dword v81, v[78:79], off
	v_add_co_u32_e32 v78, vcc, 0xffe20000, v8
	s_nop 1
	v_addc_co_u32_e32 v79, vcc, -1, v9, vcc
	global_load_dword v82, v[78:79], off
	v_add_co_u32_e32 v78, vcc, 0xffe70000, v8
	s_nop 1
	v_addc_co_u32_e32 v79, vcc, -1, v9, vcc
	global_load_dword v83, v[78:79], off
	v_add_co_u32_e32 v78, vcc, 0xffec0000, v8
	s_nop 1
	v_addc_co_u32_e32 v79, vcc, -1, v9, vcc
	global_load_dword v84, v[78:79], off
	v_add_co_u32_e32 v78, vcc, 0xfff10000, v8
	s_nop 1
	v_addc_co_u32_e32 v79, vcc, -1, v9, vcc
	global_load_dword v85, v[78:79], off
	v_add_co_u32_e32 v78, vcc, 0xfff60000, v8
	s_nop 1
	v_addc_co_u32_e32 v79, vcc, -1, v9, vcc
	global_load_dword v86, v[78:79], off
	v_add_co_u32_e32 v78, vcc, 0xfffb0000, v8
	s_nop 1
	v_addc_co_u32_e32 v79, vcc, -1, v9, vcc
	global_load_dword v87, v[78:79], off
	global_load_dword v88, v[8:9], off
	s_mov_b64 s[8:9], 0x280000
	v_lshl_add_u64 v[8:9], v[8:9], 0, s[8:9]
	v_mov_b32_e32 v79, v99
	s_waitcnt vmcnt(7)
	v_dot2c_f32_bf16_e32 v79, v81, v81
	v_dot2c_f32_bf16_e32 v79, v81, v81
	v_dot2c_f32_bf16_e32 v79, v81, v81
	v_dot2c_f32_bf16_e32 v79, v81, v81
	s_nop 2
	v_add_f32_dpp v78, v79, v79 quad_perm:[1,0,3,2] row_mask:0xf bank_mask:0xf bound_ctrl:1
	s_nop 1
	v_add_f32_dpp v78, v78, v78 quad_perm:[2,3,0,1] row_mask:0xf bank_mask:0xf bound_ctrl:1
	s_nop 1
	v_add_f32_dpp v80, v78, v78 row_half_mirror row_mask:0xf bank_mask:0xf bound_ctrl:1
	v_mov_b32_e32 v79, v99
	s_waitcnt vmcnt(6)
	v_dot2c_f32_bf16_e32 v79, v82, v82
	v_dot2c_f32_bf16_e32 v79, v82, v82
	v_dot2c_f32_bf16_e32 v79, v82, v82
	v_dot2c_f32_bf16_e32 v79, v82, v82
	s_nop 2
	v_add_f32_dpp v78, v79, v79 quad_perm:[1,0,3,2] row_mask:0xf bank_mask:0xf bound_ctrl:1
	s_nop 1
	v_add_f32_dpp v78, v78, v78 quad_perm:[2,3,0,1] row_mask:0xf bank_mask:0xf bound_ctrl:1
	s_nop 1
	v_add_f32_dpp v78, v78, v78 row_half_mirror row_mask:0xf bank_mask:0xf bound_ctrl:1
	v_max3_f32 v32, v32, v80, v78
	v_mov_b32_e32 v79, v99
	s_waitcnt vmcnt(5)
	v_dot2c_f32_bf16_e32 v79, v83, v83
	v_dot2c_f32_bf16_e32 v79, v83, v83
	v_dot2c_f32_bf16_e32 v79, v83, v83
	v_dot2c_f32_bf16_e32 v79, v83, v83
	s_nop 2
	v_add_f32_dpp v78, v79, v79 quad_perm:[1,0,3,2] row_mask:0xf bank_mask:0xf bound_ctrl:1
	s_nop 1
	v_add_f32_dpp v78, v78, v78 quad_perm:[2,3,0,1] row_mask:0xf bank_mask:0xf bound_ctrl:1
	s_nop 1
	v_add_f32_dpp v80, v78, v78 row_half_mirror row_mask:0xf bank_mask:0xf bound_ctrl:1
	v_mov_b32_e32 v79, v99
	s_waitcnt vmcnt(4)
	v_dot2c_f32_bf16_e32 v79, v84, v84
	v_dot2c_f32_bf16_e32 v79, v84, v84
	v_dot2c_f32_bf16_e32 v79, v84, v84
	v_dot2c_f32_bf16_e32 v79, v84, v84
	s_nop 2
	v_add_f32_dpp v78, v79, v79 quad_perm:[1,0,3,2] row_mask:0xf bank_mask:0xf bound_ctrl:1
	s_nop 1
	v_add_f32_dpp v78, v78, v78 quad_perm:[2,3,0,1] row_mask:0xf bank_mask:0xf bound_ctrl:1
	s_nop 1
	v_add_f32_dpp v78, v78, v78 row_half_mirror row_mask:0xf bank_mask:0xf bound_ctrl:1
	v_max3_f32 v32, v32, v80, v78
	v_mov_b32_e32 v79, v99
	s_waitcnt vmcnt(3)
	v_dot2c_f32_bf16_e32 v79, v85, v85
	v_dot2c_f32_bf16_e32 v79, v85, v85
	v_dot2c_f32_bf16_e32 v79, v85, v85
	v_dot2c_f32_bf16_e32 v79, v85, v85
	s_nop 2
	v_add_f32_dpp v78, v79, v79 quad_perm:[1,0,3,2] row_mask:0xf bank_mask:0xf bound_ctrl:1
	s_nop 1
	v_add_f32_dpp v78, v78, v78 quad_perm:[2,3,0,1] row_mask:0xf bank_mask:0xf bound_ctrl:1
	s_nop 1
	v_add_f32_dpp v80, v78, v78 row_half_mirror row_mask:0xf bank_mask:0xf bound_ctrl:1
	v_mov_b32_e32 v79, v99
	s_waitcnt vmcnt(2)
	v_dot2c_f32_bf16_e32 v79, v86, v86
	v_dot2c_f32_bf16_e32 v79, v86, v86
	v_dot2c_f32_bf16_e32 v79, v86, v86
	v_dot2c_f32_bf16_e32 v79, v86, v86
	s_nop 2
	v_add_f32_dpp v78, v79, v79 quad_perm:[1,0,3,2] row_mask:0xf bank_mask:0xf bound_ctrl:1
	s_nop 1
	v_add_f32_dpp v78, v78, v78 quad_perm:[2,3,0,1] row_mask:0xf bank_mask:0xf bound_ctrl:1
	s_nop 1
	v_add_f32_dpp v78, v78, v78 row_half_mirror row_mask:0xf bank_mask:0xf bound_ctrl:1
	v_max3_f32 v32, v32, v80, v78
	v_mov_b32_e32 v79, v99
	s_waitcnt vmcnt(1)
	v_dot2c_f32_bf16_e32 v79, v87, v87
	v_dot2c_f32_bf16_e32 v79, v87, v87
	v_dot2c_f32_bf16_e32 v79, v87, v87
	v_dot2c_f32_bf16_e32 v79, v87, v87
	s_nop 2
	v_add_f32_dpp v78, v79, v79 quad_perm:[1,0,3,2] row_mask:0xf bank_mask:0xf bound_ctrl:1
	s_nop 1
	v_add_f32_dpp v78, v78, v78 quad_perm:[2,3,0,1] row_mask:0xf bank_mask:0xf bound_ctrl:1
	s_nop 1
	v_add_f32_dpp v80, v78, v78 row_half_mirror row_mask:0xf bank_mask:0xf bound_ctrl:1
	v_mov_b32_e32 v79, v99
	s_waitcnt vmcnt(0)
	v_dot2c_f32_bf16_e32 v79, v88, v88
	v_dot2c_f32_bf16_e32 v79, v88, v88
	v_dot2c_f32_bf16_e32 v79, v88, v88
	v_dot2c_f32_bf16_e32 v79, v88, v88
	s_nop 2
	v_add_f32_dpp v78, v79, v79 quad_perm:[1,0,3,2] row_mask:0xf bank_mask:0xf bound_ctrl:1
	s_nop 1
	v_add_f32_dpp v78, v78, v78 quad_perm:[2,3,0,1] row_mask:0xf bank_mask:0xf bound_ctrl:1
	s_nop 1
	v_add_f32_dpp v78, v78, v78 row_half_mirror row_mask:0xf bank_mask:0xf bound_ctrl:1
	v_max3_f32 v32, v32, v80, v78
	s_add_i32 s1, s1, -8
	s_cmp_eq_u32 s1, 0
	s_cbranch_scc0 .LBB0_43
	v_add_f32_e32 v18, v18, v19
	v_add_f32_e32 v19, v22, v23
	v_add_f32_e32 v16, v16, v17
	v_add_f32_e32 v17, v20, v21
	v_add_f32_e32 v20, v24, v25
	v_add_f32_e32 v24, v33, v34
	v_add_f32_e32 v25, v35, v36
	v_add_f32_e32 v33, v49, v50
	v_add_f32_e32 v35, v53, v57
	s_mov_b32 s0, 0x7f61b1e6
	v_add_f32_e32 v22, v26, v27
	v_add_f32_e32 v26, v37, v38
	v_add_f32_e32 v37, v60, v61
	v_add_f32_e32 v14, v14, v15
	v_add_f32_e32 v12, v12, v13
	v_min3_f32 v13, v18, s0, v19
	v_max3_f32 v19, v33, 0, v35
	v_cmp_lt_i32_e32 vcc, v208, v204
	v_add_f32_e32 v21, v28, v29
	v_add_f32_e32 v34, v51, v52
	v_add_f32_e32 v36, v58, v59
	v_max3_f32 v16, v16, 0, v17
	v_max3_f32 v14, v19, v37, v14
	v_cndmask_b32_e32 v19, v202, v208, vcc
	v_add_f32_e32 v38, v62, v63
	v_add_f32_e32 v15, v64, v65
	v_max3_f32 v16, v16, v20, v21
	v_min3_f32 v20, v34, s0, v36
	v_lshlrev_b32_e32 v19, 2, v19
	v_add_f32_e32 v23, v30, v31
	v_add_f32_e32 v27, v39, v40
	v_add_f32_e32 v10, v10, v11
	v_add_f32_e32 v11, v66, v67
	v_add_f32_e32 v40, v70, v71
	v_min3_f32 v15, v20, v38, v15
	ds_bpermute_b32 v20, v19, v16
	v_add_f32_e32 v9, v76, v77
	v_add_f32_e32 v28, v41, v42
	v_add_f32_e32 v30, v45, v46
	v_add_f32_e32 v42, v74, v75
	v_min3_f32 v13, v13, v22, v23
	v_max3_f32 v17, v24, 0, v26
	v_min3_f32 v11, v11, s0, v40
	v_max3_f32 v17, v17, v28, v30
	v_min3_f32 v9, v11, v42, v9
	ds_bpermute_b32 v11, v19, v13
	ds_bpermute_b32 v21, v19, v17
	v_add_f32_e32 v29, v43, v44
	v_add_f32_e32 v31, v47, v48
	v_min3_f32 v18, v25, s0, v27
	v_min3_f32 v18, v18, v29, v31
	s_waitcnt lgkmcnt(2)
	v_max_f32_e32 v20, v20, v20
	v_max_f32_e32 v16, v16, v20
	ds_bpermute_b32 v20, v19, v18
	s_waitcnt lgkmcnt(2)
	v_max_f32_e32 v11, v11, v11
	v_min_f32_e32 v11, v13, v11
	s_waitcnt lgkmcnt(1)
	v_max_f32_e32 v13, v21, v21
	ds_bpermute_b32 v21, v19, v14
	v_add_f32_e32 v39, v68, v69
	v_add_f32_e32 v41, v72, v73
	v_max3_f32 v10, v10, 0, v39
	v_max_f32_e32 v13, v17, v13
	s_waitcnt lgkmcnt(1)
	v_max_f32_e32 v17, v20, v20
	v_max3_f32 v10, v10, v41, v12
	v_min_f32_e32 v17, v18, v17
	ds_bpermute_b32 v18, v19, v15
	s_waitcnt lgkmcnt(1)
	v_max_f32_e32 v20, v21, v21
	ds_bpermute_b32 v21, v19, v10
	ds_bpermute_b32 v12, v19, v32
	ds_bpermute_b32 v19, v19, v9
	s_waitcnt lgkmcnt(3)
	v_max_f32_e32 v18, v18, v18
	v_min_f32_e32 v15, v15, v18
	s_waitcnt lgkmcnt(2)
	v_max_f32_e32 v18, v21, v21
	v_max_f32_e32 v18, v10, v18
	s_waitcnt lgkmcnt(0)
	v_max_f32_e32 v10, v19, v19
	v_cmp_lt_i32_e32 vcc, v209, v204
	v_add_f32_e32 v62, v1, v0
	v_min_f32_e32 v19, v9, v10
	v_cndmask_b32_e32 v10, v202, v209, vcc
	v_add_f32_e32 v61, v2, v62
	v_max_f32_e32 v14, v14, v20
	v_lshlrev_b32_e32 v20, 2, v10
	v_add_f32_e32 v60, v61, v3
	v_max_f32_e32 v9, v12, v12
	ds_bpermute_b32 v10, v20, v16
	v_max_f32_e32 v12, v32, v32
	v_add_f32_e32 v59, v4, v60
	v_add_u32_e32 v2, -1, v202
	v_max_f32_e32 v21, v12, v9
	ds_bpermute_b32 v12, v20, v11
	v_add_f32_e32 v58, v5, v59
	v_cmp_lt_i32_e32 vcc, v2, v203
	ds_bpermute_b32 v23, v20, v13
	v_add_f32_e32 v57, v6, v58
	v_cndmask_b32_e32 v2, v2, v202, vcc
	v_add_f32_e32 v1, v7, v57
	v_lshlrev_b32_e32 v2, 2, v2
	ds_bpermute_b32 v3, v2, v1
	s_waitcnt lgkmcnt(3)
	v_max_f32_e32 v9, v10, v10
	v_max_f32_e32 v9, v16, v9
	s_waitcnt lgkmcnt(2)
	v_max_f32_e32 v10, v12, v12
	ds_bpermute_b32 v16, v20, v14
	v_min_f32_e32 v10, v11, v10
	s_waitcnt lgkmcnt(2)
	v_max_f32_e32 v11, v23, v23
	ds_bpermute_b32 v23, v20, v15
	v_and_b32_e32 v8, 63, v56
	s_waitcnt lgkmcnt(2)
	v_add_f32_e32 v3, v1, v3
	v_cmp_eq_u32_e32 vcc, 0, v8
	v_add_u32_e32 v6, -2, v202
	v_max_f32_e32 v11, v13, v11
	v_cndmask_b32_e32 v3, v3, v1, vcc
	v_cmp_lt_i32_e32 vcc, v6, v203
	s_waitcnt lgkmcnt(1)
	v_max_f32_e32 v13, v16, v16
	ds_bpermute_b32 v5, v20, v19
	v_cndmask_b32_e32 v6, v6, v202, vcc
	ds_bpermute_b32 v22, v20, v21
	v_max_f32_e32 v13, v14, v13
	s_waitcnt lgkmcnt(2)
	v_max_f32_e32 v14, v23, v23
	v_lshlrev_b32_e32 v6, 2, v6
	v_min_f32_e32 v2, v15, v14
	ds_bpermute_b32 v14, v6, v3
	s_waitcnt lgkmcnt(2)
	v_max_f32_e32 v5, v5, v5
	v_min_f32_e32 v6, v19, v5
	s_waitcnt lgkmcnt(1)
	v_max_f32_e32 v5, v22, v22
	v_max_f32_e32 v7, v21, v5
	s_waitcnt lgkmcnt(0)
	v_add_f32_e32 v5, v3, v14
	v_cmp_gt_u32_e32 vcc, 2, v8
	ds_bpermute_b32 v12, v20, v17
	ds_bpermute_b32 v16, v20, v18
	v_cndmask_b32_e32 v3, v5, v3, vcc
	v_add_u32_e32 v5, -4, v202
	v_cmp_lt_i32_e32 vcc, v5, v203
	s_waitcnt lgkmcnt(1)
	v_max_f32_e32 v12, v12, v12
	s_waitcnt lgkmcnt(0)
	v_max_f32_e32 v4, v16, v16
	v_cndmask_b32_e32 v5, v5, v202, vcc
	v_lshlrev_b32_e32 v5, 2, v5
	ds_bpermute_b32 v5, v5, v3
	v_cmp_lt_i32_e32 vcc, v210, v204
	v_min_f32_e32 v12, v17, v12
	v_max_f32_e32 v4, v18, v4
	v_cndmask_b32_e32 v14, v202, v210, vcc
	s_waitcnt lgkmcnt(0)
	v_add_f32_e32 v5, v3, v5
	v_cmp_gt_u32_e32 vcc, 4, v8
	v_lshlrev_b32_e32 v22, 2, v14
	ds_bpermute_b32 v17, v22, v7
	v_cndmask_b32_e32 v3, v5, v3, vcc
	v_add_u32_e32 v5, -8, v202
	v_cmp_lt_i32_e32 vcc, v5, v203
	ds_bpermute_b32 v14, v22, v9
	ds_bpermute_b32 v15, v22, v10
	v_cndmask_b32_e32 v5, v5, v202, vcc
	v_lshlrev_b32_e32 v5, 2, v5
	ds_bpermute_b32 v5, v5, v3
	v_cmp_gt_u32_e32 vcc, 8, v8
	ds_bpermute_b32 v16, v22, v11
	ds_bpermute_b32 v18, v22, v12
	ds_bpermute_b32 v19, v22, v13
	s_waitcnt lgkmcnt(3)
	v_add_f32_e32 v5, v3, v5
	v_cndmask_b32_e32 v3, v5, v3, vcc
	v_add_u32_e32 v5, -16, v202
	v_cmp_lt_i32_e32 vcc, v5, v203
	ds_bpermute_b32 v20, v22, v2
	ds_bpermute_b32 v21, v22, v4
	v_cndmask_b32_e32 v5, v5, v202, vcc
	v_lshlrev_b32_e32 v5, 2, v5
	ds_bpermute_b32 v5, v5, v3
	v_cmp_gt_u32_e32 vcc, 16, v8
	ds_bpermute_b32 v22, v22, v6
	v_readfirstlane_b32 s0, v56
	s_ashr_i32 s0, s0, 6
	s_waitcnt lgkmcnt(1)
	v_add_f32_e32 v5, v3, v5
	v_cndmask_b32_e32 v3, v5, v3, vcc
	v_subrev_u32_e32 v5, 32, v202
	v_cmp_lt_i32_e32 vcc, v5, v203
	s_nop 1
	v_cndmask_b32_e32 v5, v5, v202, vcc
	v_lshlrev_b32_e32 v5, 2, v5
	ds_bpermute_b32 v5, v5, v3
	v_cmp_lt_i32_e32 vcc, 62, v8
	s_waitcnt lgkmcnt(0)
	v_add_f32_e32 v5, v3, v5
	s_and_saveexec_b64 s[8:9], vcc
	s_xor_b64 s[8:9], exec, s[8:9]
	s_lshl_b32 s1, s0, 2
	s_add_i32 s1, s1, 0
	s_add_i32 s1, s1, 0x1d200
	v_mov_b32_e32 v2, s1
	ds_write_b32 v2, v5
	s_andn2_saveexec_b64 s[8:9], s[8:9]
	s_cbranch_execz .LBB0_50
	v_cmp_eq_u32_e32 vcc, 0, v8
	s_and_saveexec_b64 s[82:83], vcc
	s_cbranch_execz .LBB0_49
	v_max_f32_e32 v17, v17, v17
	v_max_f32_e32 v7, v7, v7
	v_max_f32_e32 v7, v7, v17
	v_max_f32_e32 v17, v22, v22
	v_max_f32_e32 v6, v6, v6
	v_min_f32_e32 v6, v6, v17
	v_max_f32_e32 v17, v21, v21
	v_max_f32_e32 v4, v4, v4
	s_mul_i32 s1, s0, 36
	v_max_f32_e32 v4, v4, v17
	v_max_f32_e32 v17, v20, v20
	v_max_f32_e32 v2, v2, v2
	s_add_i32 s1, s1, 0
	v_min_f32_e32 v2, v2, v17
	v_max_f32_e32 v17, v19, v19
	v_max_f32_e32 v13, v13, v13
	v_max_f32_e32 v14, v14, v14
	v_max_f32_e32 v9, v9, v9
	s_add_i32 s1, s1, 0x1d2c0
	v_max_f32_e32 v13, v13, v17
	v_max_f32_e32 v17, v18, v18
	v_max_f32_e32 v12, v12, v12
	v_max_f32_e32 v16, v16, v16
	v_max_f32_e32 v11, v11, v11
	v_max_f32_e32 v15, v15, v15
	v_max_f32_e32 v10, v10, v10
	v_max_f32_e32 v9, v9, v14
	v_mov_b32_e32 v14, s1
	v_min_f32_e32 v12, v12, v17
	v_max_f32_e32 v11, v11, v16
	v_min_f32_e32 v10, v10, v15
	ds_write_b32 v14, v7 offset:32
	ds_write2_b32 v14, v9, v11 offset1:1
	ds_write2_b32 v14, v10, v12 offset0:4 offset1:5
	ds_write2_b32 v14, v13, v4 offset0:2 offset1:3
	ds_write2_b32 v14, v2, v6 offset0:6 offset1:7
